# attention prep: all head-row loads and the q-gain load of a token issued at the top of the token iteration; iterations 1-7 have no VMEM wait
# baseline (speedup 1.0000x reference)
; __device__ __forceinline__ unsigned cvt_pk_bf16(float lo, float hi) { unsigned r; asm volatile("v_cvt_pk_bf16_f32 %0, %1, %2" : "=v"(r) : "v"(lo), "v"(hi)); return r; }
; __device__ __forceinline__ float bf_lo(unsigned v) { return __uint_as_float(v << 16); }
; __device__ __forceinline__ float bf_hi(unsigned v) { return __uint_as_float(v & 0xffff0000u); }
; __device__ __forceinline__ void prep_phase(const int TID, const int BID, PP p) {
;     ...
;         const bf16_t* r = raw + (size_t)tok * NINP; const int pos = tok & 4095;
;         float cq[4], sq[4], ci[4], si[4];
;         { const int j = lane & 3, ji = lane & 1;
; #pragma unroll
;           for (int e = 0; e < 4; ++e) {
;               rope_cs(pos, exp2f(-(float)(4 * j + e) * (L2T / 16.0f)), cq[e], sq[e]);
;               rope_cs(pos, exp2f(-(float)(4 * ji + e) * (L2T / 8.0f)), ci[e], si[e]); } }
; #pragma unroll
;         for (int it = 0; it < 10; ++it) {
;             const int head = 2 * it + (lane >> 5), j = lane & 31;
;             const bool isq = head < 16;
;             const int col = isq ? head * 128 : 2048 + (head - 16) * 128;
;             const u32x2 rw = *(const u32x2*)(r + col + 4 * j);
;             f32x4 v = (f32x4){bf_lo(rw.x), bf_hi(rw.x), bf_lo(rw.y), bf_hi(rw.y)};
;             float ss = v[0] * v[0] + v[1] * v[1] + v[2] * v[2] + v[3] * v[3];
; #pragma unroll
;             for (int o = 16; o > 0; o >>= 1) ss += __shfl_xor(ss, o);
;             const float rn = rinv_of(ss, 1.0f / 128.0f);
;             const f32x4 g4 = *(const f32x4*)((isq ? p->attn_q_gain : p->attn_k_gain) + 4 * j);
;             v = v * rn * g4;
;             f32x4 pt;
; #pragma unroll
;             for (int e = 0; e < 4; ++e) pt[e] = __shfl_xor(v[e], 4);
;             if (j < 8) {
; #pragma unroll
;                 for (int e = 0; e < 4; ++e) v[e] = (j < 4) ? v[e] * cq[e] - pt[e] * sq[e] : v[e] * cq[e] + pt[e] * sq[e];
;             }
;             u32x2 o; o.x = cvt_pk_bf16(v[0], v[1]); o.y = cvt_pk_bf16(v[2], v[3]);
;             { int w8 = __builtin_amdgcn_cvt_pk_fp8_f32(v[0], v[1], 0, false); w8 = __builtin_amdgcn_cvt_pk_fp8_f32(v[2], v[3], w8, true);
;               if (isq) *(int*)((unsigned char*)Qb + (size_t)tok * 2048 + head * 128 + 4 * j) = w8;
;               else *(int*)((unsigned char*)Kb + (size_t)tok * 512 + (head - 16) * 128 + 4 * j) = w8; }
.LBB0_748:
	v_and_b32_e32 v40, 0xfff, v62
	v_cvt_f64_u32_e32 v[40:41], v40
	s_mov_b32 s0, 0x6dc9c883
	v_mul_f64 v[42:43], v[0:1], v[40:41]
	s_mov_b32 s1, 0x3fc45f30
	v_mul_f64 v[44:45], v[42:43], s[0:1]
	v_rndne_f64_e32 v[44:45], v[44:45]
	v_fma_f64 v[42:43], v[42:43], s[0:1], -v[44:45]
	v_mul_f64 v[44:45], v[4:5], v[40:41]
	v_mul_f64 v[48:49], v[44:45], s[0:1]
	v_rndne_f64_e32 v[48:49], v[48:49]
	v_fma_f64 v[44:45], v[44:45], s[0:1], -v[48:49]
	v_cvt_f32_f64_e32 v42, v[42:43]
	v_cvt_f32_f64_e32 v43, v[44:45]
	v_mul_f64 v[44:45], v[8:9], v[40:41]
	v_mul_f64 v[50:51], v[12:13], v[40:41]
	v_mul_f64 v[48:49], v[44:45], s[0:1]
	s_waitcnt lgkmcnt(0)
	v_mul_f64 v[52:53], v[50:51], s[0:1]
	v_rndne_f64_e32 v[48:49], v[48:49]
	v_rndne_f64_e32 v[52:53], v[52:53]
	v_fma_f64 v[44:45], v[44:45], s[0:1], -v[48:49]
	v_fma_f64 v[50:51], v[50:51], s[0:1], -v[52:53]
	v_cvt_f32_f64_e32 v44, v[44:45]
	v_cvt_f32_f64_e32 v45, v[50:51]
	v_lshl_add_u64 v[50:51], s[2:3], 0, v[26:27]
	s_mov_b32 s0, 0x1b500000
	v_add_co_u32_e32 v54, vcc, s0, v50
	v_sin_f32_e32 v46, v42
	s_nop 0
	v_addc_co_u32_e32 v55, vcc, 0, v51, vcc
	global_load_dwordx2 v[56:57], v[54:55], off
	v_readlane_b32 s26, v254, 15
	v_readlane_b32 s27, v254, 16
	v_mbcnt_lo_u32_b32 v216, -1, 0
	v_mbcnt_hi_u32_b32 v216, -1, v216
	v_lshlrev_b32_e32 v216, 3, v216
	v_mov_b32_e32 v217, 0
	s_mov_b64 s[28:29], 0x2000
	v_lshl_add_u64 v[212:213], v[54:55], 0, s[26:27]
	v_lshl_add_u64 v[212:213], v[212:213], 0, v[216:217]
	v_lshl_add_u64 v[214:215], v[212:213], 0, s[28:29]
	global_load_dwordx4 v[208:211], v[212:213], off
	global_load_dwordx4 v[208:211], v[212:213], off offset:1024
	global_load_dwordx4 v[208:211], v[212:213], off offset:2048
	global_load_dwordx4 v[208:211], v[212:213], off offset:3072
	global_load_dwordx4 v[208:211], v[214:215], off offset:-4096
	global_load_dwordx4 v[208:211], v[214:215], off offset:-3072
	global_load_dwordx4 v[208:211], v[214:215], off offset:-2048
	global_load_dwordx4 v[208:211], v[214:215], off offset:-1024
	global_load_dwordx4 v[208:211], v[214:215], off
	s_mov_b64 s[30:31], 0x1000
	global_load_dwordx4 v[236:239], v[16:17], off
	global_load_dwordx2 v[218:219], v[54:55], off offset:512
	global_load_dwordx2 v[220:221], v[54:55], off offset:1024
	global_load_dwordx2 v[222:223], v[54:55], off offset:1536
	global_load_dwordx2 v[224:225], v[54:55], off offset:2048
	global_load_dwordx2 v[226:227], v[54:55], off offset:2560
	global_load_dwordx2 v[228:229], v[54:55], off offset:3072
	global_load_dwordx2 v[230:231], v[54:55], off offset:3584
	v_lshl_add_u64 v[240:241], v[54:55], 0, s[30:31]
	global_load_dwordx2 v[232:233], v[240:241], off
	global_load_dwordx2 v[234:235], v[240:241], off offset:512
	v_cos_f32_e32 v42, v42
	v_sin_f32_e32 v47, v43
	v_cos_f32_e32 v43, v43
	v_sin_f32_e32 v48, v44
	v_cos_f32_e32 v44, v44
	v_sin_f32_e32 v49, v45
	v_cos_f32_e32 v45, v45
	s_waitcnt vmcnt(0)
	v_lshlrev_b32_e32 v60, 16, v56
	v_and_b32_e32 v61, 0xffff0000, v56
	v_and_b32_e32 v52, 0xffff0000, v57
	v_pk_mul_f32 v[58:59], v[60:61], v[60:61]
	v_and_b32_e32 v53, s0, v57
	v_lshlrev_b32_e32 v57, 16, v57
	v_mov_b32_e32 v56, v52
	v_pk_mul_f32 v[68:69], v[56:57], v[56:57]
	v_add_f32_e32 v58, v58, v59
	v_add_f32_e32 v58, v69, v58
	v_add_f32_e32 v58, v68, v58
	v_mov_b64_e32 v[68:69], v[236:237]
	v_mov_b64_e32 v[70:71], v[238:239]
	ds_bpermute_b32 v59, v64, v58
	v_pk_mov_b32 v[52:53], v[56:57], v[52:53] op_sel:[1,0]
	s_waitcnt lgkmcnt(0)
	v_add_f32_e32 v58, v58, v59
	s_nop 1
	v_add_f32_dpp v58, v58, v58 row_ror:8 row_mask:0xf bank_mask:0xf
	s_nop 1
	v_add_f32_dpp v58, v58, v58 row_ror:4 row_mask:0xf bank_mask:0xf
	s_nop 1
	v_add_f32_dpp v58, v58, v58 row_ror:2 row_mask:0xf bank_mask:0xf
	s_nop 1
	v_add_f32_dpp v58, v58, v58 row_ror:1 row_mask:0xf bank_mask:0xf
	v_fmamk_f32 v58, v58, 0x3c000000, v189
	v_cmp_gt_f32_e32 vcc, s78, v58
	v_mul_f32_e32 v59, 0x4b800000, v58
	s_nop 0
	v_cndmask_b32_e32 v58, v58, v59, vcc
	v_rsq_f32_e32 v58, v58
	s_nop 0
	v_mul_f32_e32 v59, 0x45800000, v58
	v_cndmask_b32_e32 v58, v58, v59, vcc
	v_pk_mul_f32 v[60:61], v[58:59], v[60:61] op_sel_hi:[0,1]
	v_pk_mul_f32 v[52:53], v[58:59], v[52:53] op_sel_hi:[0,1]
	v_pk_mul_f32 v[52:53], v[70:71], v[52:53]
	v_pk_mul_f32 v[56:57], v[68:69], v[60:61]
	ds_bpermute_b32 v60, v63, v56
	ds_bpermute_b32 v61, v63, v57
	ds_bpermute_b32 v58, v63, v52
	ds_bpermute_b32 v59, v63, v53
	s_and_saveexec_b64 s[22:23], s[8:9]
	s_cbranch_execz .LBB0_750
	s_waitcnt lgkmcnt(2)
	v_pk_mul_f32 v[60:61], v[46:47], v[60:61]
	s_waitcnt lgkmcnt(0)
	v_pk_mul_f32 v[58:59], v[48:49], v[58:59]
	v_cndmask_b32_e64 v61, v61, -v61, s[10:11]
	v_cndmask_b32_e64 v60, v60, -v60, s[10:11]
	v_cndmask_b32_e64 v59, v59, -v59, s[10:11]
	v_cndmask_b32_e64 v58, v58, -v58, s[10:11]
	v_pk_fma_f32 v[56:57], v[42:43], v[56:57], v[60:61]
	v_pk_fma_f32 v[52:53], v[44:45], v[52:53], v[58:59]
; __device__ __forceinline__ unsigned cvt_pk_bf16(float lo, float hi) { unsigned r; asm volatile("v_cvt_pk_bf16_f32 %0, %1, %2" : "=v"(r) : "v"(lo), "v"(hi)); return r; }
; __device__ __forceinline__ float bf_lo(unsigned v) { return __uint_as_float(v << 16); }
; __device__ __forceinline__ float bf_hi(unsigned v) { return __uint_as_float(v & 0xffff0000u); }
; __device__ __forceinline__ float rinv_of(float ss, float invn) { return rsqrtf(ss * invn + 1e-6f); }
; __device__ __forceinline__ void prep_phase(const int TID, const int BID, PP p) {
;     ...
;         for (int it = 0; it < 10; ++it) {
;             const int head = 2 * it + (lane >> 5), j = lane & 31;
;             const bool isq = head < 16;
;             const int col = isq ? head * 128 : 2048 + (head - 16) * 128;
;             const u32x2 rw = *(const u32x2*)(r + col + 4 * j);
;             f32x4 v = (f32x4){bf_lo(rw.x), bf_hi(rw.x), bf_lo(rw.y), bf_hi(rw.y)};
;             float ss = v[0] * v[0] + v[1] * v[1] + v[2] * v[2] + v[3] * v[3];
; #pragma unroll
;             for (int o = 16; o > 0; o >>= 1) ss += __shfl_xor(ss, o);
;             const float rn = rinv_of(ss, 1.0f / 128.0f);
;             const f32x4 g4 = *(const f32x4*)((isq ? p->attn_q_gain : p->attn_k_gain) + 4 * j);
;             v = v * rn * g4;
;             f32x4 pt;
; #pragma unroll
;             for (int e = 0; e < 4; ++e) pt[e] = __shfl_xor(v[e], 4);
;             if (j < 8) {
; #pragma unroll
;                 for (int e = 0; e < 4; ++e) v[e] = (j < 4) ? v[e] * cq[e] - pt[e] * sq[e] : v[e] * cq[e] + pt[e] * sq[e];
;             }
;             u32x2 o; o.x = cvt_pk_bf16(v[0], v[1]); o.y = cvt_pk_bf16(v[2], v[3]);
;             { int w8 = __builtin_amdgcn_cvt_pk_fp8_f32(v[0], v[1], 0, false); w8 = __builtin_amdgcn_cvt_pk_fp8_f32(v[2], v[3], w8, true);
;               if (isq) *(int*)((unsigned char*)Qb + (size_t)tok * 2048 + head * 128 + 4 * j) = w8;
;               else *(int*)((unsigned char*)Kb + (size_t)tok * 512 + (head - 16) * 128 + 4 * j) = w8; }
.LBB0_750:
	s_or_b64 exec, exec, s[22:23]
	s_waitcnt lgkmcnt(1)
	v_cvt_pk_bf16_f32 v58, v56, v57
	s_nop 0
	v_cvt_pk_bf16_f32 v58, v52, v53
	s_nop 0
	v_mov_b32_e32 v58, v161
	v_cvt_pk_fp8_f32 v58, v56, v57
	v_cvt_pk_fp8_f32 v58, v52, v53 op_sel:[0,0,1]
	v_lshl_add_u64 v[52:53], s[2:3], 0, v[38:39]
	global_store_dword v[52:53], v58, off offset:-1024
	s_waitcnt lgkmcnt(0)
	v_mov_b64_e32 v[56:57], v[236:237]
	v_mov_b64_e32 v[58:59], v[238:239]
	s_nop 0
	v_mov_b64_e32 v[54:55], v[218:219]
	v_lshlrev_b32_e32 v60, 16, v54
	v_and_b32_e32 v61, 0xffff0000, v54
	v_and_b32_e32 v70, 0xffff0000, v55
	v_pk_mul_f32 v[68:69], v[60:61], v[60:61]
	v_and_b32_e32 v71, s0, v55
	v_lshlrev_b32_e32 v55, 16, v55
	v_mov_b32_e32 v54, v70
	v_pk_mul_f32 v[72:73], v[54:55], v[54:55]
	v_add_f32_e32 v68, v68, v69
	v_add_f32_e32 v68, v73, v68
	v_add_f32_e32 v68, v72, v68
	ds_bpermute_b32 v69, v64, v68
	v_pk_mov_b32 v[54:55], v[54:55], v[70:71] op_sel:[1,0]
	s_waitcnt lgkmcnt(0)
	v_add_f32_e32 v68, v68, v69
	s_nop 1
	v_add_f32_dpp v68, v68, v68 row_ror:8 row_mask:0xf bank_mask:0xf
	s_nop 1
	v_add_f32_dpp v68, v68, v68 row_ror:4 row_mask:0xf bank_mask:0xf
	s_nop 1
	v_add_f32_dpp v68, v68, v68 row_ror:2 row_mask:0xf bank_mask:0xf
	s_nop 1
	v_add_f32_dpp v68, v68, v68 row_ror:1 row_mask:0xf bank_mask:0xf
	v_fmamk_f32 v68, v68, 0x3c000000, v189
	v_cmp_gt_f32_e32 vcc, s78, v68
	v_mul_f32_e32 v69, 0x4b800000, v68
	s_nop 0
	v_cndmask_b32_e32 v68, v68, v69, vcc
	v_rsq_f32_e32 v68, v68
	s_nop 0
	v_mul_f32_e32 v69, 0x45800000, v68
	v_cndmask_b32_e32 v68, v68, v69, vcc
	v_pk_mul_f32 v[60:61], v[68:69], v[60:61] op_sel_hi:[0,1]
	v_pk_mul_f32 v[54:55], v[68:69], v[54:55] op_sel_hi:[0,1]
	v_pk_mul_f32 v[54:55], v[58:59], v[54:55]
	v_pk_mul_f32 v[56:57], v[56:57], v[60:61]
	ds_bpermute_b32 v60, v63, v56
	ds_bpermute_b32 v61, v63, v57
	ds_bpermute_b32 v58, v63, v54
	ds_bpermute_b32 v59, v63, v55
	s_and_saveexec_b64 s[22:23], s[8:9]
	s_cbranch_execz .LBB0_752
	s_waitcnt lgkmcnt(2)
	v_pk_mul_f32 v[60:61], v[46:47], v[60:61]
	s_waitcnt lgkmcnt(0)
	v_pk_mul_f32 v[58:59], v[48:49], v[58:59]
	v_cndmask_b32_e64 v61, v61, -v61, s[10:11]
	v_cndmask_b32_e64 v60, v60, -v60, s[10:11]
	v_cndmask_b32_e64 v59, v59, -v59, s[10:11]
	v_cndmask_b32_e64 v58, v58, -v58, s[10:11]
	v_pk_fma_f32 v[56:57], v[42:43], v[56:57], v[60:61]
	v_pk_fma_f32 v[54:55], v[44:45], v[54:55], v[58:59]
.LBB0_752:
	s_or_b64 exec, exec, s[22:23]
	s_waitcnt lgkmcnt(1)
	v_cvt_pk_bf16_f32 v58, v56, v57
	s_nop 0
	v_cvt_pk_bf16_f32 v58, v54, v55
	s_nop 0
	v_mov_b32_e32 v58, v161
	v_cvt_pk_fp8_f32 v58, v56, v57
	v_cvt_pk_fp8_f32 v58, v54, v55 op_sel:[0,0,1]
	v_add_co_u32_e32 v54, vcc, 0x1b500000, v50
	global_store_dword v[52:53], v58, off offset:-768
	s_nop 0
	v_addc_co_u32_e32 v55, vcc, 0, v51, vcc
	v_mov_b64_e32 v[54:55], v[220:221]
	v_lshlrev_b32_e32 v60, 16, v54
	s_waitcnt lgkmcnt(0)
	v_mov_b64_e32 v[56:57], v[236:237]
	v_mov_b64_e32 v[58:59], v[238:239]
	v_and_b32_e32 v61, 0xffff0000, v54
	v_and_b32_e32 v70, 0xffff0000, v55
	v_pk_mul_f32 v[68:69], v[60:61], v[60:61]
	v_and_b32_e32 v71, s0, v55
	v_lshlrev_b32_e32 v55, 16, v55
	v_mov_b32_e32 v54, v70
	v_pk_mul_f32 v[72:73], v[54:55], v[54:55]
	v_add_f32_e32 v68, v68, v69
	v_add_f32_e32 v68, v73, v68
	v_add_f32_e32 v68, v72, v68
	ds_bpermute_b32 v69, v64, v68
	v_pk_mov_b32 v[54:55], v[54:55], v[70:71] op_sel:[1,0]
	s_waitcnt lgkmcnt(0)
	v_add_f32_e32 v68, v68, v69
	s_nop 1
	v_add_f32_dpp v68, v68, v68 row_ror:8 row_mask:0xf bank_mask:0xf
	s_nop 1
	v_add_f32_dpp v68, v68, v68 row_ror:4 row_mask:0xf bank_mask:0xf
	s_nop 1
	v_add_f32_dpp v68, v68, v68 row_ror:2 row_mask:0xf bank_mask:0xf
	s_nop 1
	v_add_f32_dpp v68, v68, v68 row_ror:1 row_mask:0xf bank_mask:0xf
	v_fmamk_f32 v68, v68, 0x3c000000, v189
	v_cmp_gt_f32_e32 vcc, s78, v68
	v_mul_f32_e32 v69, 0x4b800000, v68
	s_nop 0
	v_cndmask_b32_e32 v68, v68, v69, vcc
	v_rsq_f32_e32 v68, v68
	s_nop 0
	v_mul_f32_e32 v69, 0x45800000, v68
	v_cndmask_b32_e32 v68, v68, v69, vcc
	v_pk_mul_f32 v[60:61], v[68:69], v[60:61] op_sel_hi:[0,1]
	v_pk_mul_f32 v[54:55], v[68:69], v[54:55] op_sel_hi:[0,1]
	v_pk_mul_f32 v[54:55], v[58:59], v[54:55]
	v_pk_mul_f32 v[56:57], v[56:57], v[60:61]
	ds_bpermute_b32 v60, v63, v56
	ds_bpermute_b32 v61, v63, v57
	ds_bpermute_b32 v58, v63, v54
	ds_bpermute_b32 v59, v63, v55
	s_and_saveexec_b64 s[22:23], s[8:9]
	s_cbranch_execz .LBB0_754
	s_waitcnt lgkmcnt(2)
	v_pk_mul_f32 v[60:61], v[46:47], v[60:61]
	s_waitcnt lgkmcnt(0)
	v_pk_mul_f32 v[58:59], v[48:49], v[58:59]
	v_cndmask_b32_e64 v61, v61, -v61, s[10:11]
	v_cndmask_b32_e64 v60, v60, -v60, s[10:11]
	v_cndmask_b32_e64 v59, v59, -v59, s[10:11]
	v_cndmask_b32_e64 v58, v58, -v58, s[10:11]
	v_pk_fma_f32 v[56:57], v[42:43], v[56:57], v[60:61]
	v_pk_fma_f32 v[54:55], v[44:45], v[54:55], v[58:59]
; __device__ __forceinline__ unsigned cvt_pk_bf16(float lo, float hi) { unsigned r; asm volatile("v_cvt_pk_bf16_f32 %0, %1, %2" : "=v"(r) : "v"(lo), "v"(hi)); return r; }
; __device__ __forceinline__ float bf_lo(unsigned v) { return __uint_as_float(v << 16); }
; __device__ __forceinline__ float bf_hi(unsigned v) { return __uint_as_float(v & 0xffff0000u); }
; __device__ __forceinline__ float rinv_of(float ss, float invn) { return rsqrtf(ss * invn + 1e-6f); }
; __device__ __forceinline__ void prep_phase(const int TID, const int BID, PP p) {
;     ...
;         for (int it = 0; it < 10; ++it) {
;             const int head = 2 * it + (lane >> 5), j = lane & 31;
;             const bool isq = head < 16;
;             const int col = isq ? head * 128 : 2048 + (head - 16) * 128;
;             const u32x2 rw = *(const u32x2*)(r + col + 4 * j);
;             f32x4 v = (f32x4){bf_lo(rw.x), bf_hi(rw.x), bf_lo(rw.y), bf_hi(rw.y)};
;             float ss = v[0] * v[0] + v[1] * v[1] + v[2] * v[2] + v[3] * v[3];
; #pragma unroll
;             for (int o = 16; o > 0; o >>= 1) ss += __shfl_xor(ss, o);
;             const float rn = rinv_of(ss, 1.0f / 128.0f);
;             const f32x4 g4 = *(const f32x4*)((isq ? p->attn_q_gain : p->attn_k_gain) + 4 * j);
;             v = v * rn * g4;
;             f32x4 pt;
; #pragma unroll
;             for (int e = 0; e < 4; ++e) pt[e] = __shfl_xor(v[e], 4);
;             if (j < 8) {
; #pragma unroll
;                 for (int e = 0; e < 4; ++e) v[e] = (j < 4) ? v[e] * cq[e] - pt[e] * sq[e] : v[e] * cq[e] + pt[e] * sq[e];
;             }
;             u32x2 o; o.x = cvt_pk_bf16(v[0], v[1]); o.y = cvt_pk_bf16(v[2], v[3]);
;             { int w8 = __builtin_amdgcn_cvt_pk_fp8_f32(v[0], v[1], 0, false); w8 = __builtin_amdgcn_cvt_pk_fp8_f32(v[2], v[3], w8, true);
;               if (isq) *(int*)((unsigned char*)Qb + (size_t)tok * 2048 + head * 128 + 4 * j) = w8;
;               else *(int*)((unsigned char*)Kb + (size_t)tok * 512 + (head - 16) * 128 + 4 * j) = w8; }
.LBB0_754:
	s_or_b64 exec, exec, s[22:23]
	s_waitcnt lgkmcnt(1)
	v_cvt_pk_bf16_f32 v58, v56, v57
	s_nop 0
	v_cvt_pk_bf16_f32 v58, v54, v55
	s_nop 0
	v_mov_b32_e32 v58, v161
	v_cvt_pk_fp8_f32 v58, v56, v57
	v_cvt_pk_fp8_f32 v58, v54, v55 op_sel:[0,0,1]
	v_add_co_u32_e32 v54, vcc, 0x1b500000, v50
	global_store_dword v[52:53], v58, off offset:-512
	s_nop 0
	v_addc_co_u32_e32 v55, vcc, 0, v51, vcc
	v_mov_b64_e32 v[54:55], v[222:223]
	v_lshlrev_b32_e32 v60, 16, v54
	s_waitcnt lgkmcnt(0)
	v_mov_b64_e32 v[56:57], v[236:237]
	v_mov_b64_e32 v[58:59], v[238:239]
	v_and_b32_e32 v61, 0xffff0000, v54
	v_and_b32_e32 v70, 0xffff0000, v55
	v_pk_mul_f32 v[68:69], v[60:61], v[60:61]
	v_and_b32_e32 v71, s0, v55
	v_lshlrev_b32_e32 v55, 16, v55
	v_mov_b32_e32 v54, v70
	v_pk_mul_f32 v[72:73], v[54:55], v[54:55]
	v_add_f32_e32 v68, v68, v69
	v_add_f32_e32 v68, v73, v68
	v_add_f32_e32 v68, v72, v68
	ds_bpermute_b32 v69, v64, v68
	v_pk_mov_b32 v[54:55], v[54:55], v[70:71] op_sel:[1,0]
	s_waitcnt lgkmcnt(0)
	v_add_f32_e32 v68, v68, v69
	s_nop 1
	v_add_f32_dpp v68, v68, v68 row_ror:8 row_mask:0xf bank_mask:0xf
	s_nop 1
	v_add_f32_dpp v68, v68, v68 row_ror:4 row_mask:0xf bank_mask:0xf
	s_nop 1
	v_add_f32_dpp v68, v68, v68 row_ror:2 row_mask:0xf bank_mask:0xf
	s_nop 1
	v_add_f32_dpp v68, v68, v68 row_ror:1 row_mask:0xf bank_mask:0xf
	v_fmamk_f32 v68, v68, 0x3c000000, v189
	v_cmp_gt_f32_e32 vcc, s78, v68
	v_mul_f32_e32 v69, 0x4b800000, v68
	s_nop 0
	v_cndmask_b32_e32 v68, v68, v69, vcc
	v_rsq_f32_e32 v68, v68
	s_nop 0
	v_mul_f32_e32 v69, 0x45800000, v68
	v_cndmask_b32_e32 v68, v68, v69, vcc
	v_pk_mul_f32 v[60:61], v[68:69], v[60:61] op_sel_hi:[0,1]
	v_pk_mul_f32 v[54:55], v[68:69], v[54:55] op_sel_hi:[0,1]
	v_pk_mul_f32 v[54:55], v[58:59], v[54:55]
	v_pk_mul_f32 v[56:57], v[56:57], v[60:61]
	ds_bpermute_b32 v60, v63, v56
	ds_bpermute_b32 v61, v63, v57
	ds_bpermute_b32 v58, v63, v54
	ds_bpermute_b32 v59, v63, v55
	s_and_saveexec_b64 s[22:23], s[8:9]
	s_cbranch_execz .LBB0_756
	s_waitcnt lgkmcnt(2)
	v_pk_mul_f32 v[60:61], v[46:47], v[60:61]
	s_waitcnt lgkmcnt(0)
	v_pk_mul_f32 v[58:59], v[48:49], v[58:59]
	v_cndmask_b32_e64 v61, v61, -v61, s[10:11]
	v_cndmask_b32_e64 v60, v60, -v60, s[10:11]
	v_cndmask_b32_e64 v59, v59, -v59, s[10:11]
	v_cndmask_b32_e64 v58, v58, -v58, s[10:11]
	v_pk_fma_f32 v[56:57], v[42:43], v[56:57], v[60:61]
	v_pk_fma_f32 v[54:55], v[44:45], v[54:55], v[58:59]
.LBB0_756:
	s_or_b64 exec, exec, s[22:23]
	s_waitcnt lgkmcnt(1)
	v_cvt_pk_bf16_f32 v58, v56, v57
	s_nop 0
	v_cvt_pk_bf16_f32 v58, v54, v55
	s_nop 0
	v_mov_b32_e32 v58, v161
	v_cvt_pk_fp8_f32 v58, v56, v57
	v_cvt_pk_fp8_f32 v58, v54, v55 op_sel:[0,0,1]
	v_add_co_u32_e32 v54, vcc, 0x1b500000, v50
	global_store_dword v[52:53], v58, off offset:-256
	s_nop 0
	v_addc_co_u32_e32 v55, vcc, 0, v51, vcc
	v_mov_b64_e32 v[54:55], v[224:225]
	v_lshlrev_b32_e32 v60, 16, v54
	s_waitcnt lgkmcnt(0)
	v_mov_b64_e32 v[56:57], v[236:237]
	v_mov_b64_e32 v[58:59], v[238:239]
	v_and_b32_e32 v61, 0xffff0000, v54
	v_and_b32_e32 v70, 0xffff0000, v55
	v_pk_mul_f32 v[68:69], v[60:61], v[60:61]
	v_and_b32_e32 v71, s0, v55
	v_lshlrev_b32_e32 v55, 16, v55
	v_mov_b32_e32 v54, v70
	v_pk_mul_f32 v[72:73], v[54:55], v[54:55]
	v_add_f32_e32 v68, v68, v69
	v_add_f32_e32 v68, v73, v68
	v_add_f32_e32 v68, v72, v68
	ds_bpermute_b32 v69, v64, v68
	v_pk_mov_b32 v[54:55], v[54:55], v[70:71] op_sel:[1,0]
	s_waitcnt lgkmcnt(0)
	v_add_f32_e32 v68, v68, v69
	s_nop 1
	v_add_f32_dpp v68, v68, v68 row_ror:8 row_mask:0xf bank_mask:0xf
	s_nop 1
	v_add_f32_dpp v68, v68, v68 row_ror:4 row_mask:0xf bank_mask:0xf
	s_nop 1
	v_add_f32_dpp v68, v68, v68 row_ror:2 row_mask:0xf bank_mask:0xf
	s_nop 1
	v_add_f32_dpp v68, v68, v68 row_ror:1 row_mask:0xf bank_mask:0xf
	v_fmamk_f32 v68, v68, 0x3c000000, v189
	v_cmp_gt_f32_e32 vcc, s78, v68
	v_mul_f32_e32 v69, 0x4b800000, v68
	s_nop 0
	v_cndmask_b32_e32 v68, v68, v69, vcc
	v_rsq_f32_e32 v68, v68
	s_nop 0
	v_mul_f32_e32 v69, 0x45800000, v68
	v_cndmask_b32_e32 v68, v68, v69, vcc
	v_pk_mul_f32 v[60:61], v[68:69], v[60:61] op_sel_hi:[0,1]
	v_pk_mul_f32 v[54:55], v[68:69], v[54:55] op_sel_hi:[0,1]
	v_pk_mul_f32 v[54:55], v[58:59], v[54:55]
	v_pk_mul_f32 v[56:57], v[56:57], v[60:61]
	ds_bpermute_b32 v60, v63, v56
	ds_bpermute_b32 v61, v63, v57
	ds_bpermute_b32 v58, v63, v54
	ds_bpermute_b32 v59, v63, v55
	s_and_saveexec_b64 s[22:23], s[8:9]
	s_cbranch_execz .LBB0_758
	s_waitcnt lgkmcnt(2)
	v_pk_mul_f32 v[60:61], v[46:47], v[60:61]
	s_waitcnt lgkmcnt(0)
	v_pk_mul_f32 v[58:59], v[48:49], v[58:59]
	v_cndmask_b32_e64 v61, v61, -v61, s[10:11]
	v_cndmask_b32_e64 v60, v60, -v60, s[10:11]
	v_cndmask_b32_e64 v59, v59, -v59, s[10:11]
	v_cndmask_b32_e64 v58, v58, -v58, s[10:11]
	v_pk_fma_f32 v[56:57], v[42:43], v[56:57], v[60:61]
	v_pk_fma_f32 v[54:55], v[44:45], v[54:55], v[58:59]
; __device__ __forceinline__ unsigned cvt_pk_bf16(float lo, float hi) { unsigned r; asm volatile("v_cvt_pk_bf16_f32 %0, %1, %2" : "=v"(r) : "v"(lo), "v"(hi)); return r; }
; __device__ __forceinline__ float bf_lo(unsigned v) { return __uint_as_float(v << 16); }
; __device__ __forceinline__ float bf_hi(unsigned v) { return __uint_as_float(v & 0xffff0000u); }
; __device__ __forceinline__ float rinv_of(float ss, float invn) { return rsqrtf(ss * invn + 1e-6f); }
; __device__ __forceinline__ void prep_phase(const int TID, const int BID, PP p) {
;     ...
;         for (int it = 0; it < 10; ++it) {
;             const int head = 2 * it + (lane >> 5), j = lane & 31;
;             const bool isq = head < 16;
;             const int col = isq ? head * 128 : 2048 + (head - 16) * 128;
;             const u32x2 rw = *(const u32x2*)(r + col + 4 * j);
;             f32x4 v = (f32x4){bf_lo(rw.x), bf_hi(rw.x), bf_lo(rw.y), bf_hi(rw.y)};
;             float ss = v[0] * v[0] + v[1] * v[1] + v[2] * v[2] + v[3] * v[3];
; #pragma unroll
;             for (int o = 16; o > 0; o >>= 1) ss += __shfl_xor(ss, o);
;             const float rn = rinv_of(ss, 1.0f / 128.0f);
;             const f32x4 g4 = *(const f32x4*)((isq ? p->attn_q_gain : p->attn_k_gain) + 4 * j);
;             v = v * rn * g4;
;             f32x4 pt;
; #pragma unroll
;             for (int e = 0; e < 4; ++e) pt[e] = __shfl_xor(v[e], 4);
;             if (j < 8) {
; #pragma unroll
;                 for (int e = 0; e < 4; ++e) v[e] = (j < 4) ? v[e] * cq[e] - pt[e] * sq[e] : v[e] * cq[e] + pt[e] * sq[e];
;             }
;             u32x2 o; o.x = cvt_pk_bf16(v[0], v[1]); o.y = cvt_pk_bf16(v[2], v[3]);
;             { int w8 = __builtin_amdgcn_cvt_pk_fp8_f32(v[0], v[1], 0, false); w8 = __builtin_amdgcn_cvt_pk_fp8_f32(v[2], v[3], w8, true);
;               if (isq) *(int*)((unsigned char*)Qb + (size_t)tok * 2048 + head * 128 + 4 * j) = w8;
;               else *(int*)((unsigned char*)Kb + (size_t)tok * 512 + (head - 16) * 128 + 4 * j) = w8; }
.LBB0_758:
	s_or_b64 exec, exec, s[22:23]
	s_waitcnt lgkmcnt(1)
	v_cvt_pk_bf16_f32 v58, v56, v57
	s_nop 0
	v_cvt_pk_bf16_f32 v58, v54, v55
	s_nop 0
	v_mov_b32_e32 v58, v161
	v_cvt_pk_fp8_f32 v58, v56, v57
	v_cvt_pk_fp8_f32 v58, v54, v55 op_sel:[0,0,1]
	v_add_co_u32_e32 v54, vcc, 0x1b500000, v50
	global_store_dword v[52:53], v58, off
	s_nop 0
	v_addc_co_u32_e32 v55, vcc, 0, v51, vcc
	v_mov_b64_e32 v[54:55], v[226:227]
	v_lshlrev_b32_e32 v60, 16, v54
	s_waitcnt lgkmcnt(0)
	v_mov_b64_e32 v[56:57], v[236:237]
	v_mov_b64_e32 v[58:59], v[238:239]
	v_and_b32_e32 v61, 0xffff0000, v54
	v_and_b32_e32 v70, 0xffff0000, v55
	v_pk_mul_f32 v[68:69], v[60:61], v[60:61]
	v_and_b32_e32 v71, s0, v55
	v_lshlrev_b32_e32 v55, 16, v55
	v_mov_b32_e32 v54, v70
	v_pk_mul_f32 v[72:73], v[54:55], v[54:55]
	v_add_f32_e32 v68, v68, v69
	v_add_f32_e32 v68, v73, v68
	v_add_f32_e32 v68, v72, v68
	ds_bpermute_b32 v69, v64, v68
	v_pk_mov_b32 v[54:55], v[54:55], v[70:71] op_sel:[1,0]
	s_waitcnt lgkmcnt(0)
	v_add_f32_e32 v68, v68, v69
	s_nop 1
	v_add_f32_dpp v68, v68, v68 row_ror:8 row_mask:0xf bank_mask:0xf
	s_nop 1
	v_add_f32_dpp v68, v68, v68 row_ror:4 row_mask:0xf bank_mask:0xf
	s_nop 1
	v_add_f32_dpp v68, v68, v68 row_ror:2 row_mask:0xf bank_mask:0xf
	s_nop 1
	v_add_f32_dpp v68, v68, v68 row_ror:1 row_mask:0xf bank_mask:0xf
	v_fmamk_f32 v68, v68, 0x3c000000, v189
	v_cmp_gt_f32_e32 vcc, s78, v68
	v_mul_f32_e32 v69, 0x4b800000, v68
	s_nop 0
	v_cndmask_b32_e32 v68, v68, v69, vcc
	v_rsq_f32_e32 v68, v68
	s_nop 0
	v_mul_f32_e32 v69, 0x45800000, v68
	v_cndmask_b32_e32 v68, v68, v69, vcc
	v_pk_mul_f32 v[60:61], v[68:69], v[60:61] op_sel_hi:[0,1]
	v_pk_mul_f32 v[54:55], v[68:69], v[54:55] op_sel_hi:[0,1]
	v_pk_mul_f32 v[54:55], v[58:59], v[54:55]
	v_pk_mul_f32 v[56:57], v[56:57], v[60:61]
	ds_bpermute_b32 v60, v63, v56
	ds_bpermute_b32 v61, v63, v57
	ds_bpermute_b32 v58, v63, v54
	ds_bpermute_b32 v59, v63, v55
	s_and_saveexec_b64 s[22:23], s[8:9]
	s_cbranch_execz .LBB0_760
	s_waitcnt lgkmcnt(2)
	v_pk_mul_f32 v[60:61], v[46:47], v[60:61]
	s_waitcnt lgkmcnt(0)
	v_pk_mul_f32 v[58:59], v[48:49], v[58:59]
	v_cndmask_b32_e64 v61, v61, -v61, s[10:11]
	v_cndmask_b32_e64 v60, v60, -v60, s[10:11]
	v_cndmask_b32_e64 v59, v59, -v59, s[10:11]
	v_cndmask_b32_e64 v58, v58, -v58, s[10:11]
	v_pk_fma_f32 v[56:57], v[42:43], v[56:57], v[60:61]
	v_pk_fma_f32 v[54:55], v[44:45], v[54:55], v[58:59]
.LBB0_760:
	s_or_b64 exec, exec, s[22:23]
	s_waitcnt lgkmcnt(1)
	v_cvt_pk_bf16_f32 v58, v56, v57
	s_nop 0
	v_cvt_pk_bf16_f32 v58, v54, v55
	s_nop 0
	v_mov_b32_e32 v58, v161
	v_cvt_pk_fp8_f32 v58, v56, v57
	v_cvt_pk_fp8_f32 v58, v54, v55 op_sel:[0,0,1]
	v_add_co_u32_e32 v54, vcc, 0x1b500000, v50
	global_store_dword v[52:53], v58, off offset:256
	s_nop 0
	v_addc_co_u32_e32 v55, vcc, 0, v51, vcc
	v_mov_b64_e32 v[54:55], v[228:229]
	v_lshlrev_b32_e32 v60, 16, v54
	s_waitcnt lgkmcnt(0)
	v_mov_b64_e32 v[56:57], v[236:237]
	v_mov_b64_e32 v[58:59], v[238:239]
	v_and_b32_e32 v61, 0xffff0000, v54
	v_and_b32_e32 v70, 0xffff0000, v55
	v_pk_mul_f32 v[68:69], v[60:61], v[60:61]
	v_and_b32_e32 v71, s0, v55
	v_lshlrev_b32_e32 v55, 16, v55
	v_mov_b32_e32 v54, v70
	v_pk_mul_f32 v[72:73], v[54:55], v[54:55]
	v_add_f32_e32 v68, v68, v69
	v_add_f32_e32 v68, v73, v68
	v_add_f32_e32 v68, v72, v68
	ds_bpermute_b32 v69, v64, v68
	v_pk_mov_b32 v[54:55], v[54:55], v[70:71] op_sel:[1,0]
	s_waitcnt lgkmcnt(0)
	v_add_f32_e32 v68, v68, v69
	s_nop 1
	v_add_f32_dpp v68, v68, v68 row_ror:8 row_mask:0xf bank_mask:0xf
	s_nop 1
	v_add_f32_dpp v68, v68, v68 row_ror:4 row_mask:0xf bank_mask:0xf
	s_nop 1
	v_add_f32_dpp v68, v68, v68 row_ror:2 row_mask:0xf bank_mask:0xf
	s_nop 1
	v_add_f32_dpp v68, v68, v68 row_ror:1 row_mask:0xf bank_mask:0xf
	v_fmamk_f32 v68, v68, 0x3c000000, v189
	v_cmp_gt_f32_e32 vcc, s78, v68
	v_mul_f32_e32 v69, 0x4b800000, v68
	s_nop 0
	v_cndmask_b32_e32 v68, v68, v69, vcc
	v_rsq_f32_e32 v68, v68
	s_nop 0
	v_mul_f32_e32 v69, 0x45800000, v68
	v_cndmask_b32_e32 v68, v68, v69, vcc
	v_pk_mul_f32 v[60:61], v[68:69], v[60:61] op_sel_hi:[0,1]
	v_pk_mul_f32 v[54:55], v[68:69], v[54:55] op_sel_hi:[0,1]
	v_pk_mul_f32 v[54:55], v[58:59], v[54:55]
	v_pk_mul_f32 v[56:57], v[56:57], v[60:61]
	ds_bpermute_b32 v60, v63, v56
	ds_bpermute_b32 v61, v63, v57
	ds_bpermute_b32 v58, v63, v54
	ds_bpermute_b32 v59, v63, v55
	s_and_saveexec_b64 s[22:23], s[8:9]
	s_cbranch_execz .LBB0_762
	s_waitcnt lgkmcnt(2)
	v_pk_mul_f32 v[60:61], v[46:47], v[60:61]
	s_waitcnt lgkmcnt(0)
	v_pk_mul_f32 v[58:59], v[48:49], v[58:59]
	v_cndmask_b32_e64 v61, v61, -v61, s[10:11]
	v_cndmask_b32_e64 v60, v60, -v60, s[10:11]
	v_cndmask_b32_e64 v59, v59, -v59, s[10:11]
	v_cndmask_b32_e64 v58, v58, -v58, s[10:11]
	v_pk_fma_f32 v[56:57], v[42:43], v[56:57], v[60:61]
	v_pk_fma_f32 v[54:55], v[44:45], v[54:55], v[58:59]
; __device__ __forceinline__ unsigned cvt_pk_bf16(float lo, float hi) { unsigned r; asm volatile("v_cvt_pk_bf16_f32 %0, %1, %2" : "=v"(r) : "v"(lo), "v"(hi)); return r; }
; __device__ __forceinline__ float bf_lo(unsigned v) { return __uint_as_float(v << 16); }
; __device__ __forceinline__ float bf_hi(unsigned v) { return __uint_as_float(v & 0xffff0000u); }
; __device__ __forceinline__ float rinv_of(float ss, float invn) { return rsqrtf(ss * invn + 1e-6f); }
; __device__ __forceinline__ void prep_phase(const int TID, const int BID, PP p) {
;     ...
;         for (int it = 0; it < 10; ++it) {
;             const int head = 2 * it + (lane >> 5), j = lane & 31;
;             const bool isq = head < 16;
;             const int col = isq ? head * 128 : 2048 + (head - 16) * 128;
;             const u32x2 rw = *(const u32x2*)(r + col + 4 * j);
;             f32x4 v = (f32x4){bf_lo(rw.x), bf_hi(rw.x), bf_lo(rw.y), bf_hi(rw.y)};
;             float ss = v[0] * v[0] + v[1] * v[1] + v[2] * v[2] + v[3] * v[3];
; #pragma unroll
;             for (int o = 16; o > 0; o >>= 1) ss += __shfl_xor(ss, o);
;             const float rn = rinv_of(ss, 1.0f / 128.0f);
;             const f32x4 g4 = *(const f32x4*)((isq ? p->attn_q_gain : p->attn_k_gain) + 4 * j);
;             v = v * rn * g4;
;             f32x4 pt;
; #pragma unroll
;             for (int e = 0; e < 4; ++e) pt[e] = __shfl_xor(v[e], 4);
;             if (j < 8) {
; #pragma unroll
;                 for (int e = 0; e < 4; ++e) v[e] = (j < 4) ? v[e] * cq[e] - pt[e] * sq[e] : v[e] * cq[e] + pt[e] * sq[e];
;             }
;             u32x2 o; o.x = cvt_pk_bf16(v[0], v[1]); o.y = cvt_pk_bf16(v[2], v[3]);
;             { int w8 = __builtin_amdgcn_cvt_pk_fp8_f32(v[0], v[1], 0, false); w8 = __builtin_amdgcn_cvt_pk_fp8_f32(v[2], v[3], w8, true);
;               if (isq) *(int*)((unsigned char*)Qb + (size_t)tok * 2048 + head * 128 + 4 * j) = w8;
;               else *(int*)((unsigned char*)Kb + (size_t)tok * 512 + (head - 16) * 128 + 4 * j) = w8; }
.LBB0_762:
	s_or_b64 exec, exec, s[22:23]
	s_waitcnt lgkmcnt(1)
	v_cvt_pk_bf16_f32 v58, v56, v57
	s_nop 0
	v_cvt_pk_bf16_f32 v58, v54, v55
	s_nop 0
	v_mov_b32_e32 v58, v161
	v_cvt_pk_fp8_f32 v58, v56, v57
	v_cvt_pk_fp8_f32 v58, v54, v55 op_sel:[0,0,1]
	v_add_co_u32_e32 v54, vcc, 0x1b500000, v50
	global_store_dword v[52:53], v58, off offset:512
	s_nop 0
	v_addc_co_u32_e32 v55, vcc, 0, v51, vcc
	v_mov_b64_e32 v[54:55], v[230:231]
	v_lshlrev_b32_e32 v60, 16, v54
	s_waitcnt lgkmcnt(0)
	v_mov_b64_e32 v[56:57], v[236:237]
	v_mov_b64_e32 v[58:59], v[238:239]
	v_and_b32_e32 v61, 0xffff0000, v54
	v_and_b32_e32 v70, 0xffff0000, v55
	v_pk_mul_f32 v[68:69], v[60:61], v[60:61]
	v_and_b32_e32 v71, s0, v55
	v_lshlrev_b32_e32 v55, 16, v55
	v_mov_b32_e32 v54, v70
	v_pk_mul_f32 v[72:73], v[54:55], v[54:55]
	v_add_f32_e32 v68, v68, v69
	v_add_f32_e32 v68, v73, v68
	v_add_f32_e32 v68, v72, v68
	ds_bpermute_b32 v69, v64, v68
	v_pk_mov_b32 v[54:55], v[54:55], v[70:71] op_sel:[1,0]
	s_waitcnt lgkmcnt(0)
	v_add_f32_e32 v68, v68, v69
	s_nop 1
	v_add_f32_dpp v68, v68, v68 row_ror:8 row_mask:0xf bank_mask:0xf
	s_nop 1
	v_add_f32_dpp v68, v68, v68 row_ror:4 row_mask:0xf bank_mask:0xf
	s_nop 1
	v_add_f32_dpp v68, v68, v68 row_ror:2 row_mask:0xf bank_mask:0xf
	s_nop 1
	v_add_f32_dpp v68, v68, v68 row_ror:1 row_mask:0xf bank_mask:0xf
	v_fmamk_f32 v68, v68, 0x3c000000, v189
	v_cmp_gt_f32_e32 vcc, s78, v68
	v_mul_f32_e32 v69, 0x4b800000, v68
	s_nop 0
	v_cndmask_b32_e32 v68, v68, v69, vcc
	v_rsq_f32_e32 v68, v68
	s_nop 0
	v_mul_f32_e32 v69, 0x45800000, v68
	v_cndmask_b32_e32 v68, v68, v69, vcc
	v_pk_mul_f32 v[60:61], v[68:69], v[60:61] op_sel_hi:[0,1]
	v_pk_mul_f32 v[54:55], v[68:69], v[54:55] op_sel_hi:[0,1]
	v_pk_mul_f32 v[54:55], v[58:59], v[54:55]
	v_pk_mul_f32 v[56:57], v[56:57], v[60:61]
	ds_bpermute_b32 v60, v63, v56
	ds_bpermute_b32 v61, v63, v57
	ds_bpermute_b32 v58, v63, v54
	ds_bpermute_b32 v59, v63, v55
	s_and_saveexec_b64 s[22:23], s[8:9]
	s_cbranch_execz .LBB0_764
	s_waitcnt lgkmcnt(2)
	v_pk_mul_f32 v[60:61], v[46:47], v[60:61]
	s_waitcnt lgkmcnt(0)
	v_pk_mul_f32 v[58:59], v[48:49], v[58:59]
	v_cndmask_b32_e64 v61, v61, -v61, s[10:11]
	v_cndmask_b32_e64 v60, v60, -v60, s[10:11]
	v_cndmask_b32_e64 v59, v59, -v59, s[10:11]
	v_cndmask_b32_e64 v58, v58, -v58, s[10:11]
	v_pk_fma_f32 v[56:57], v[42:43], v[56:57], v[60:61]
	v_pk_fma_f32 v[54:55], v[44:45], v[54:55], v[58:59]
.LBB0_764:
	s_or_b64 exec, exec, s[22:23]
	s_waitcnt lgkmcnt(1)
	v_cvt_pk_bf16_f32 v58, v56, v57
	s_nop 0
	v_cvt_pk_bf16_f32 v58, v54, v55
	s_nop 0
	v_mov_b32_e32 v58, v161
	v_cvt_pk_fp8_f32 v58, v56, v57
	v_cvt_pk_fp8_f32 v58, v54, v55 op_sel:[0,0,1]
	global_store_dword v[52:53], v58, off offset:768
	v_add_co_u32_e32 v52, vcc, 0x1b501000, v50
	s_nop 1
	v_addc_co_u32_e32 v53, vcc, 0, v51, vcc
	v_mov_b64_e32 v[54:55], v[232:233]
	v_lshlrev_b32_e32 v58, 16, v54
	s_waitcnt lgkmcnt(0)
	v_and_b32_e32 v59, 0xffff0000, v54
	v_and_b32_e32 v52, 0xffff0000, v55
	v_pk_mul_f32 v[56:57], v[58:59], v[58:59]
	v_lshlrev_b32_e32 v61, 16, v55
	v_mov_b32_e32 v60, v52
	v_and_b32_e32 v53, s0, v55
	v_pk_mul_f32 v[54:55], v[60:61], v[60:61]
	v_add_f32_e32 v56, v56, v57
	v_add_f32_e32 v55, v55, v56
	v_add_f32_e32 v54, v54, v55
	ds_bpermute_b32 v55, v64, v54
	v_readlane_b32 s0, v254, 32
	v_readlane_b32 s1, v254, 33
	s_load_dwordx2 s[22:23], s[0:1], 0x38
	v_pk_mov_b32 v[52:53], v[60:61], v[52:53] op_sel:[1,0]
	s_waitcnt lgkmcnt(0)
	v_add_f32_e32 v54, v54, v55
	s_nop 1
	v_add_f32_dpp v54, v54, v54 row_ror:8 row_mask:0xf bank_mask:0xf
	s_nop 1
	v_add_f32_dpp v54, v54, v54 row_ror:4 row_mask:0xf bank_mask:0xf
	s_nop 1
	v_add_f32_dpp v54, v54, v54 row_ror:2 row_mask:0xf bank_mask:0xf
	s_nop 1
	v_add_f32_dpp v54, v54, v54 row_ror:1 row_mask:0xf bank_mask:0xf
	v_fmamk_f32 v54, v54, 0x3c000000, v189
	v_cmp_gt_f32_e32 vcc, s78, v54
	v_mul_f32_e32 v55, 0x4b800000, v54
	s_nop 0
	v_cndmask_b32_e32 v54, v54, v55, vcc
	v_rsq_f32_e32 v54, v54
	s_nop 0
	v_mul_f32_e32 v55, 0x45800000, v54
	v_cndmask_b32_e32 v68, v54, v55, vcc
	global_load_dwordx4 v[54:57], v160, s[22:23]
	v_pk_mul_f32 v[58:59], v[68:69], v[58:59] op_sel_hi:[0,1]
	v_pk_mul_f32 v[52:53], v[68:69], v[52:53] op_sel_hi:[0,1]
	s_waitcnt vmcnt(0)
	v_pk_mul_f32 v[52:53], v[56:57], v[52:53]
	v_pk_mul_f32 v[54:55], v[54:55], v[58:59]
	ds_bpermute_b32 v58, v63, v54
	ds_bpermute_b32 v59, v63, v55
	ds_bpermute_b32 v56, v63, v52
	ds_bpermute_b32 v57, v63, v53
	s_and_saveexec_b64 s[24:25], s[8:9]
	s_cbranch_execz .LBB0_766
	s_waitcnt lgkmcnt(2)
	v_pk_mul_f32 v[58:59], v[46:47], v[58:59]
	s_waitcnt lgkmcnt(0)
	v_pk_mul_f32 v[56:57], v[48:49], v[56:57]
	v_cndmask_b32_e64 v59, v59, -v59, s[10:11]
	v_cndmask_b32_e64 v58, v58, -v58, s[10:11]
	v_cndmask_b32_e64 v57, v57, -v57, s[10:11]
	v_cndmask_b32_e64 v56, v56, -v56, s[10:11]
	v_pk_fma_f32 v[54:55], v[42:43], v[54:55], v[58:59]
	v_pk_fma_f32 v[52:53], v[44:45], v[52:53], v[56:57]
; __device__ __forceinline__ unsigned cvt_pk_bf16(float lo, float hi) { unsigned r; asm volatile("v_cvt_pk_bf16_f32 %0, %1, %2" : "=v"(r) : "v"(lo), "v"(hi)); return r; }
; __device__ __forceinline__ float bf_lo(unsigned v) { return __uint_as_float(v << 16); }
; __device__ __forceinline__ float bf_hi(unsigned v) { return __uint_as_float(v & 0xffff0000u); }
; __device__ __forceinline__ float rinv_of(float ss, float invn) { return rsqrtf(ss * invn + 1e-6f); }
; __device__ __forceinline__ void prep_phase(const int TID, const int BID, PP p) {
;     ...
;         for (int it = 0; it < 10; ++it) {
;             const int head = 2 * it + (lane >> 5), j = lane & 31;
;             const bool isq = head < 16;
;             const int col = isq ? head * 128 : 2048 + (head - 16) * 128;
;             const u32x2 rw = *(const u32x2*)(r + col + 4 * j);
;             f32x4 v = (f32x4){bf_lo(rw.x), bf_hi(rw.x), bf_lo(rw.y), bf_hi(rw.y)};
;             float ss = v[0] * v[0] + v[1] * v[1] + v[2] * v[2] + v[3] * v[3];
; #pragma unroll
;             for (int o = 16; o > 0; o >>= 1) ss += __shfl_xor(ss, o);
;             const float rn = rinv_of(ss, 1.0f / 128.0f);
;             const f32x4 g4 = *(const f32x4*)((isq ? p->attn_q_gain : p->attn_k_gain) + 4 * j);
;             v = v * rn * g4;
;             f32x4 pt;
; #pragma unroll
;             for (int e = 0; e < 4; ++e) pt[e] = __shfl_xor(v[e], 4);
;             if (j < 8) {
; #pragma unroll
;                 for (int e = 0; e < 4; ++e) v[e] = (j < 4) ? v[e] * cq[e] - pt[e] * sq[e] : v[e] * cq[e] + pt[e] * sq[e];
;             }
;             u32x2 o; o.x = cvt_pk_bf16(v[0], v[1]); o.y = cvt_pk_bf16(v[2], v[3]);
;             { int w8 = __builtin_amdgcn_cvt_pk_fp8_f32(v[0], v[1], 0, false); w8 = __builtin_amdgcn_cvt_pk_fp8_f32(v[2], v[3], w8, true);
;               if (isq) *(int*)((unsigned char*)Qb + (size_t)tok * 2048 + head * 128 + 4 * j) = w8;
;               else *(int*)((unsigned char*)Kb + (size_t)tok * 512 + (head - 16) * 128 + 4 * j) = w8; }
.LBB0_766:
	s_or_b64 exec, exec, s[24:25]
	s_waitcnt lgkmcnt(3)
	v_cvt_pk_bf16_f32 v58, v54, v55
	s_mov_b32 s0, 0x1b501000
	v_cvt_pk_bf16_f32 v58, v52, v53
	s_waitcnt lgkmcnt(0)
	v_lshl_add_u64 v[56:57], s[22:23], 0, v[160:161]
	v_mov_b32_e32 v58, v161
	v_cvt_pk_fp8_f32 v58, v54, v55
	v_cvt_pk_fp8_f32 v58, v52, v53 op_sel:[0,0,1]
	v_lshl_add_u64 v[52:53], s[2:3], 0, v[34:35]
	v_add_co_u32_e32 v52, vcc, s63, v52
	s_nop 1
	v_addc_co_u32_e32 v53, vcc, 0, v53, vcc
	v_add_co_u32_e32 v50, vcc, s0, v50
	global_store_dword v[52:53], v58, off
	s_nop 0
	v_addc_co_u32_e32 v51, vcc, 0, v51, vcc
	v_mov_b64_e32 v[50:51], v[234:235]
	v_lshlrev_b32_e32 v58, 16, v50
	global_load_dwordx4 v[54:57], v[56:57], off
	v_and_b32_e32 v59, 0xffff0000, v50
	v_and_b32_e32 v68, 0xffff0000, v51
	v_pk_mul_f32 v[60:61], v[58:59], v[58:59]
	v_and_b32_e32 v69, s0, v51
	v_lshlrev_b32_e32 v51, 16, v51
	v_mov_b32_e32 v50, v68
	v_pk_mul_f32 v[70:71], v[50:51], v[50:51]
	v_add_f32_e32 v60, v60, v61
	v_add_f32_e32 v60, v71, v60
	v_add_f32_e32 v60, v70, v60
	ds_bpermute_b32 v61, v64, v60
	v_pk_mov_b32 v[50:51], v[50:51], v[68:69] op_sel:[1,0]
	s_waitcnt lgkmcnt(0)
	v_add_f32_e32 v60, v60, v61
	s_nop 1
	v_add_f32_dpp v60, v60, v60 row_ror:8 row_mask:0xf bank_mask:0xf
	s_nop 1
	v_add_f32_dpp v60, v60, v60 row_ror:4 row_mask:0xf bank_mask:0xf
	s_nop 1
	v_add_f32_dpp v60, v60, v60 row_ror:2 row_mask:0xf bank_mask:0xf
	s_nop 1
	v_add_f32_dpp v60, v60, v60 row_ror:1 row_mask:0xf bank_mask:0xf
	v_fmamk_f32 v60, v60, 0x3c000000, v189
	v_cmp_gt_f32_e32 vcc, s78, v60
	v_mul_f32_e32 v61, 0x4b800000, v60
	s_nop 0
	v_cndmask_b32_e32 v60, v60, v61, vcc
	v_rsq_f32_e32 v60, v60
	s_nop 0
	v_mul_f32_e32 v61, 0x45800000, v60
	v_cndmask_b32_e32 v60, v60, v61, vcc
	v_pk_mul_f32 v[58:59], v[60:61], v[58:59] op_sel_hi:[0,1]
	v_pk_mul_f32 v[50:51], v[60:61], v[50:51] op_sel_hi:[0,1]
	s_waitcnt vmcnt(0)
	v_pk_mul_f32 v[50:51], v[56:57], v[50:51]
	v_pk_mul_f32 v[54:55], v[54:55], v[58:59]
	ds_bpermute_b32 v58, v63, v54
	ds_bpermute_b32 v59, v63, v55
	ds_bpermute_b32 v56, v63, v50
	ds_bpermute_b32 v57, v63, v51
	s_and_saveexec_b64 s[22:23], s[8:9]
	s_cbranch_execz .LBB0_768
	s_waitcnt lgkmcnt(2)
	v_pk_mul_f32 v[46:47], v[46:47], v[58:59]
	s_nop 0
	v_cndmask_b32_e64 v47, v47, -v47, s[10:11]
	v_cndmask_b32_e64 v46, v46, -v46, s[10:11]
	v_pk_fma_f32 v[54:55], v[42:43], v[54:55], v[46:47]
	s_waitcnt lgkmcnt(0)
	v_pk_mul_f32 v[42:43], v[48:49], v[56:57]
	s_nop 0
	v_cndmask_b32_e64 v43, v43, -v43, s[10:11]
	v_cndmask_b32_e64 v42, v42, -v42, s[10:11]
	v_pk_fma_f32 v[50:51], v[44:45], v[50:51], v[42:43]
